# speedup vs baseline: 1.0081x; 1.0010x over previous
; DEVI f32x16 mfma32(bf16x8 a, bf16x8 b, f32x16 c) { return __builtin_amdgcn_mfma_f32_32x32x16_bf16(a, b, c, 0, 0, 0); }
; template <bool SBK>
; __device__ __forceinline__ void attn_item(KP p, int layer, int b, int hh, int qt, char* smem, int tix) {
;     ...
;         float ps = 0.f;
; #pragma unroll
;         for (int kb2 = 0; kb2 < 2; ++kb2)
; #pragma unroll
;           for (int r = 0; r < 16; ++r) { float e = __builtin_amdgcn_exp2f(s[kb2][r] - m_run); s[kb2][r] = e; ps += e; }
;         l_run += ps;
;     ...
; #pragma unroll
;       for (int kb2 = 0; kb2 < 2; ++kb2)
; #pragma unroll
;         for (int s2 = 0; s2 < 2; ++s2) {
;           float tmp[8];
; #pragma unroll
;           for (int e = 0; e < 8; ++e) tmp[e] = s[kb2][8 * s2 + e];
;           pf[kb2][s2] = pack8(tmp);
;         }
;       asm volatile("s_nop 4" ::: "memory");
;       __builtin_amdgcn_s_setprio(1);
; #pragma unroll
;       for (int d = 0; d < NDV; ++d) {
;         const int vrow = (SBK ? c * 64 : 0) + d * 32 + l32;
; #pragma unroll
;         for (int kb2 = 0; kb2 < 2; ++kb2)
; #pragma unroll
;           for (int s2 = 0; s2 < 2; ++s2) {
;             const u16* vp = vb + vrow * VST + kb2 * 32 + 16 * s2 + 4 * hf;
;             bf16x4 lo = *(const bf16x4*)vp, hi = *(const bf16x4*)(vp + 8);
;             bf16x8 a = __builtin_shufflevector(lo, hi, 0, 1, 2, 3, 4, 5, 6, 7);
;             O[d] = mfma32(a, pf[kb2][s2], O[d]);
;           }
;       }
.LBB0_392:
	v_sub_f32_e32 v82, v82, v155
	v_exp_f32_e32 v82, v82
	v_sub_f32_e32 v83, v83, v155
	v_exp_f32_e32 v83, v83
	v_sub_f32_e32 v84, v84, v155
	v_exp_f32_e32 v84, v84
	v_sub_f32_e32 v85, v85, v155
	v_exp_f32_e32 v85, v85
	v_sub_f32_e32 v86, v86, v155
	v_add_f32_e32 v161, 0, v82
	v_exp_f32_e32 v86, v86
	v_sub_f32_e32 v87, v87, v155
	v_sub_f32_e32 v66, v66, v155
	v_add_f32_e32 v161, v83, v161
	v_exp_f32_e32 v87, v87
	v_sub_f32_e32 v88, v88, v155
	v_exp_f32_e32 v162, v66
	v_sub_f32_e32 v66, v67, v155
	v_add_f32_e32 v161, v84, v161
	v_exp_f32_e32 v88, v88
	v_sub_f32_e32 v89, v89, v155
	v_exp_f32_e32 v163, v66
	v_sub_f32_e32 v66, v68, v155
	v_add_f32_e32 v161, v85, v161
	v_exp_f32_e32 v89, v89
	v_sub_f32_e32 v90, v90, v155
	v_exp_f32_e32 v164, v66
	v_sub_f32_e32 v66, v69, v155
	v_add_f32_e32 v161, v86, v161
	v_exp_f32_e32 v90, v90
	v_sub_f32_e32 v91, v91, v155
	v_exp_f32_e32 v165, v66
	v_sub_f32_e32 v66, v70, v155
	v_add_f32_e32 v161, v87, v161
	v_exp_f32_e32 v91, v91
	v_sub_f32_e32 v92, v92, v155
	v_exp_f32_e32 v166, v66
	v_sub_f32_e32 v66, v71, v155
	v_add_f32_e32 v161, v88, v161
	v_exp_f32_e32 v92, v92
	v_sub_f32_e32 v93, v93, v155
	v_exp_f32_e32 v167, v66
	v_sub_f32_e32 v66, v72, v155
	v_add_f32_e32 v161, v89, v161
	v_exp_f32_e32 v93, v93
	v_sub_f32_e32 v94, v94, v155
	v_exp_f32_e32 v183, v66
	v_sub_f32_e32 v66, v73, v155
	v_add_f32_e32 v161, v90, v161
	v_exp_f32_e32 v94, v94
	v_sub_f32_e32 v95, v95, v155
	v_exp_f32_e32 v184, v66
	v_sub_f32_e32 v66, v74, v155
	v_add_f32_e32 v161, v91, v161
	v_exp_f32_e32 v95, v95
	v_sub_f32_e32 v96, v96, v155
	v_exp_f32_e32 v185, v66
	v_sub_f32_e32 v66, v75, v155
	v_add_f32_e32 v161, v92, v161
	v_exp_f32_e32 v96, v96
	v_sub_f32_e32 v97, v97, v155
	v_exp_f32_e32 v186, v66
	v_sub_f32_e32 v66, v76, v155
	v_add_f32_e32 v161, v93, v161
	v_exp_f32_e32 v97, v97
	v_exp_f32_e32 v187, v66
	v_sub_f32_e32 v66, v77, v155
	v_add_f32_e32 v161, v94, v161
	v_exp_f32_e32 v188, v66
	v_sub_f32_e32 v66, v78, v155
	v_add_f32_e32 v161, v95, v161
	v_exp_f32_e32 v189, v66
	v_sub_f32_e32 v66, v79, v155
	v_add_f32_e32 v161, v96, v161
	v_exp_f32_e32 v190, v66
	v_sub_f32_e32 v66, v80, v155
	v_add_f32_e32 v161, v97, v161
	v_exp_f32_e32 v191, v66
	v_sub_f32_e32 v66, v81, v155
	v_exp_f32_e32 v192, v66
	v_cvt_pk_bf16_f32 v66, v82, v83
	v_add_f32_e32 v82, v162, v161
	v_add_f32_e32 v82, v163, v82
	v_add_f32_e32 v82, v164, v82
	v_add_f32_e32 v82, v165, v82
	v_add_f32_e32 v82, v166, v82
	v_add_f32_e32 v82, v167, v82
	v_add_f32_e32 v82, v183, v82
	v_add_f32_e32 v82, v184, v82
	v_add_f32_e32 v82, v185, v82
	v_add_f32_e32 v82, v186, v82
	v_add_f32_e32 v82, v187, v82
	v_add_f32_e32 v82, v188, v82
	v_add_f32_e32 v82, v189, v82
	s_nop 4
	v_add_f32_e32 v82, v190, v82
	v_add_f32_e32 v82, v191, v82
	v_cvt_pk_bf16_f32 v67, v84, v85
	v_cvt_pk_bf16_f32 v68, v86, v87
	v_cvt_pk_bf16_f32 v69, v88, v89
	v_cvt_pk_bf16_f32 v70, v90, v91
	v_cvt_pk_bf16_f32 v71, v92, v93
	v_cvt_pk_bf16_f32 v72, v94, v95
	v_cvt_pk_bf16_f32 v73, v96, v97
	v_cvt_pk_bf16_f32 v74, v162, v163
	v_cvt_pk_bf16_f32 v75, v164, v165
	v_cvt_pk_bf16_f32 v76, v166, v167
	v_cvt_pk_bf16_f32 v77, v183, v184
	v_cvt_pk_bf16_f32 v78, v185, v186
	v_cvt_pk_bf16_f32 v79, v187, v188
	v_cvt_pk_bf16_f32 v80, v189, v190
	v_cvt_pk_bf16_f32 v81, v191, v192
	v_add_f32_e32 v86, v192, v82
	v_add_u32_e32 v243, 0xb800, v242
	s_waitcnt lgkmcnt(0)
	ds_read2_b64 v[82:85], v243 offset0:96 offset1:98
	ds_read2_b64 v[90:93], v243 offset0:100 offset1:102
	ds_read2_b64 v[94:97], v243 offset0:104 offset1:106
	ds_read2_b64 v[162:165], v243 offset0:108 offset1:110
	v_add_f32_e32 v156, v156, v86
	v_mfma_f32_32x32x16_bf16 v[50:65], v[194:197], v[66:69], v[50:65]
	v_mfma_f32_32x32x16_bf16 v[50:65], v[198:201], v[70:73], v[50:65]
	v_mfma_f32_32x32x16_bf16 v[50:65], v[202:205], v[74:77], v[50:65]
	v_mfma_f32_32x32x16_bf16 v[50:65], v[206:209], v[78:81], v[50:65]
	v_mfma_f32_32x32x16_bf16 v[34:49], v[210:213], v[66:69], v[34:49]
	v_mfma_f32_32x32x16_bf16 v[34:49], v[214:217], v[70:73], v[34:49]
	v_mfma_f32_32x32x16_bf16 v[34:49], v[218:221], v[74:77], v[34:49]
	v_mfma_f32_32x32x16_bf16 v[34:49], v[222:225], v[78:81], v[34:49]
	v_mfma_f32_32x32x16_bf16 v[18:33], v[226:229], v[66:69], v[18:33]
	v_mfma_f32_32x32x16_bf16 v[18:33], v[230:233], v[70:73], v[18:33]
	v_mfma_f32_32x32x16_bf16 v[18:33], v[234:237], v[74:77], v[18:33]
	v_mfma_f32_32x32x16_bf16 v[18:33], v[238:241], v[78:81], v[18:33]
	s_waitcnt lgkmcnt(0)
	v_mfma_f32_32x32x16_bf16 v[2:17], v[82:85], v[66:69], v[2:17]
	v_mfma_f32_32x32x16_bf16 v[2:17], v[90:93], v[70:73], v[2:17]
	v_mfma_f32_32x32x16_bf16 v[2:17], v[94:97], v[74:77], v[2:17]
	v_mfma_f32_32x32x16_bf16 v[2:17], v[162:165], v[78:81], v[2:17]
